# stagger: odd panels start P9 about 7 us late so that one half's HBM-bound GEMM epilogues fall into the other half's K-loops (panel barriers keep the offset through P10)
# speedup vs baseline: 1.0008x; 1.0008x over previous
;     __host__ __device__ void init(int M, int N, int G_, int c_) { S.init(M, N, G_, c_); nM = M / BM; nN = N / BM; }
;     __host__ __device__ bool next(int i, Unit& u) const { if (i > 1) return false; Unit b; if (!S.next(0, b)) return false; u.pm = b.pm + i * nM; u.pn = b.pn + i * nN; return true; }
; #define PH(k) if (IN(k)) for (int rep_ = 0; rep_ <= ((PROBE_REPEAT >> (k)) & 1); ++rep_)
; #define REPBAR() do { if (rep_) xcd_barrier(bar); } while (0)
;     __host__ __device__ bool next(int i, Unit& u) const {
;         const long L = (long)i * G + c; if (L >= nwg) return false;
;         int wgid = (int)L; { const int q = nwg / NXCD, r = nwg % NXCD, xcd = wgid % NXCD, off = wgid / NXCD; wgid = (xcd < r ? xcd * (q + 1) : r * (q + 1) + (xcd - r) * q) + off; }
;         const int nig = WGM * nN, gid = wgid / nig, fm = gid * WGM, gsz = (nM - fm) < WGM ? (nM - fm) : WGM;
;         u.pm = fm + ((wgid % nig) % gsz); u.pn = (wgid % nig) / gsz; return true;
; __global__ void __launch_bounds__(512, 2) mega(MegaArgs a) {
;     ...
;     PH(9) { REPBAR();
;         const pg8::Gemm& gm = gh; pg8::StaticOrder S; S.init(M, 3072, G, bid);
.LBB0_772:
	s_cmp_lt_i32 s86, 10
	s_cselect_b64 s[0:1], -1, 0
	s_cmp_gt_i32 s87, 9
	s_cselect_b64 s[2:3], -1, 0
	s_and_b64 s[0:1], s[0:1], s[2:3]
	s_andn2_b64 vcc, exec, s[0:1]
	v_readlane_b32 s64, v250, 29
	v_readlane_b32 s65, v250, 30
	s_cbranch_vccnz .LBB0_822
	v_readlane_b32 s98, v250, 28
	s_nop 0
	s_bitcmp1_b32 s98, 6
	s_cbranch_scc0 .Lstag_done
	s_sleep 127
	s_sleep 127
.Lstag_done:
	s_nop 0
	v_readlane_b32 s2, v250, 39
	s_waitcnt vmcnt(0)
	v_mov_b32_e32 v10, v0
	v_readlane_b32 s3, v250, 40
	s_and_b64 vcc, exec, s[2:3]
	s_waitcnt lgkmcnt(0)
	v_readfirstlane_b32 s14, v10
	s_cbranch_vccz .LBB0_775
	v_readlane_b32 s2, v252, 11
	s_ashr_i32 s2, s2, 4
	v_readlane_b32 s3, v252, 12
	s_add_i32 s2, s2, s3
	s_lshl_b32 s3, s2, 3
	s_mulk_i32 s2, 0x60
	v_readlane_b32 s4, v252, 13
	s_sub_i32 s2, s4, s2
	s_bfe_i32 s4, s2, 0x80000
	s_bfe_u32 s4, s4, 0x3000c
	s_add_i32 s4, s2, s4
	s_bfe_i32 s5, s4, 0x80000
	s_and_b32 s4, s4, 0xf8
	s_sub_i32 s2, s2, s4
	s_sext_i32_i16 s5, s5
	s_sext_i32_i8 s2, s2
	s_add_i32 s40, s3, s2
	s_ashr_i32 s38, s5, 3
